# final candidate: M-interval trim, SGPR-base LDS-DMA without loader VALU, counted lgkmcnt, pipelined converter read-back, FFN2-up conversion beside w_in (FFN2-down conversion back beside FFN2 gate-up)
# speedup vs baseline: 1.0046x; 1.0046x over previous
; #define LAS __attribute__((address_space(3)))
; __device__ __forceinline__ void p0_item_load(const float* __restrict__ W, int N, int nblk, int nb0, int item, int lane, f32x4 (&v)[8]) {
;     const int kb = item / nblk, nb = nb0 + item % nblk;
;     const float* src = W + (size_t)(64 * kb + (lane >> 3)) * N + 32 * nb + 4 * (lane & 7);
; #pragma unroll
;     for (int i = 0; i < 8; ++i) v[i] = __builtin_nontemporal_load((const f32x4*)(src + (size_t)(8 * i) * N));
; }
; __device__ __forceinline__ void p0_item_store(const f32x4 (&v)[8], int K, int nblk, int nb0, bf16* __restrict__ WT, int mode, LAS float* scr, int item, int lane) {
;     const int kb = item / nblk, nb = nb0 + item % nblk, k0 = 64 * kb, n0 = 32 * nb;
; #pragma unroll
;     for (int i = 0; i < 8; ++i) { LAS float* d = scr + (8 * i + (lane >> 3)) * 33 + 4 * (lane & 7); d[0] = v[i].x; d[1] = v[i].y; d[2] = v[i].z; d[3] = v[i].w; }
;     LDS_WAIT(); asm volatile("" ::: "memory");
;     const int c = lane & 7, r0 = map_row(n0, mode);
;     const float wsc = mode == 1 ? 1.44269504089f : (mode == 2 ? 0.69314718056f : 1.0f);
; #pragma unroll
;     for (int j = 0; j < 4; ++j) { const int n = (lane >> 3) + 8 * j; const LAS float* s = scr + (8 * c) * 33 + n;
;         v4u o; o.x = cvt_pk_bf16(s[0 * 33] * wsc, s[1 * 33] * wsc); o.y = cvt_pk_bf16(s[2 * 33] * wsc, s[3 * 33] * wsc); o.z = cvt_pk_bf16(s[4 * 33] * wsc, s[5 * 33] * wsc); o.w = cvt_pk_bf16(s[6 * 33] * wsc, s[7 * 33] * wsc);
;         *(v4u*)(WT + (size_t)(r0 + n) * K + k0 + 8 * c) = o; }
;     LDS_WAIT(); asm volatile("" ::: "memory");
; }
;     LAS float* scr = (LAS float*)(F.lds + RING_OFF + F.wave * 16384);
;     const int nblk = nbn ? nbn : N / 32, nall = (K / 64) * nblk, nitems = (int)((long)nall * f1 / 16);
;     int it = (int)((long)nall * f0 / 16) + w0; if (it >= nitems) return;
;     f32x4 va[8], vb[8], vc[8];
;     __builtin_amdgcn_s_waitcnt(0x0F70);
;     const int last = nitems - 1, ntri = ((nitems - it + nw - 1) / nw + 2) / 3;
;     int i1 = min(it + nw, last);
;     p0_item_load(W, N, nblk, nb0, it, F.lane, va);
;     p0_item_load(W, N, nblk, nb0, i1, F.lane, vb); __builtin_amdgcn_sched_barrier(0);
;     for (int p = 0; p < ntri; ++p) {
;         const int i2 = min(i1 + nw, last), i3 = min(i2 + nw, last), i4 = min(i3 + nw, last);
;         p0_item_load(W, N, nblk, nb0, i2, F.lane, vc); __builtin_amdgcn_sched_barrier(0);
.LBB0_101:
	s_add_i32 s2, s5, s17
	s_min_i32 s27, s2, 0x55ff
	s_ashr_i32 s2, s27, 31
	s_lshr_b32 s2, s2, 25
	s_add_i32 s2, s27, s2
	s_ashr_i32 s3, s2, 7
	s_lshl_b32 s4, s3, 6
	s_and_b32 s2, s2, 0x7ffff80
	v_or_b32_e32 v66, s4, v116
	s_sub_i32 s2, s27, s2
	v_ashrrev_i32_e32 v67, 31, v66
	v_lshlrev_b64 v[66:67], 14, v[66:67]
	s_lshl_b32 s2, s2, 5
	v_lshl_add_u64 v[66:67], s[86:87], 0, v[66:67]
	s_ashr_i32 s3, s2, 31
	v_lshl_add_u64 v[66:67], s[2:3], 2, v[66:67]
	v_lshl_add_u64 v[90:91], v[66:67], 0, v[100:101]
	v_add_co_u32_e32 v70, vcc, s10, v90
	s_add_i32 s27, s27, s17
	s_nop 0
	v_addc_co_u32_e32 v71, vcc, 0, v91, vcc
	v_add_co_u32_e32 v74, vcc, s11, v90
	global_load_dwordx4 v[66:69], v[90:91], off nt
	s_nop 0
	global_load_dwordx4 v[70:73], v[70:71], off nt
	v_addc_co_u32_e32 v75, vcc, 0, v91, vcc
	v_add_co_u32_e32 v78, vcc, s12, v90
	s_min_i32 s3, s27, 0x55ff
	s_nop 0
	v_addc_co_u32_e32 v79, vcc, 0, v91, vcc
	v_add_co_u32_e32 v82, vcc, s13, v90
	global_load_dwordx4 v[74:77], v[74:75], off nt
	s_nop 0
	global_load_dwordx4 v[78:81], v[78:79], off nt
	v_addc_co_u32_e32 v83, vcc, 0, v91, vcc
	v_add_co_u32_e32 v86, vcc, s14, v90
	s_add_i32 s27, s3, s17
	s_nop 0
	v_addc_co_u32_e32 v87, vcc, 0, v91, vcc
	v_add_co_u32_e32 v92, vcc, s15, v90
	global_load_dwordx4 v[82:85], v[82:83], off nt
	s_nop 0
	global_load_dwordx4 v[86:89], v[86:87], off nt
	v_addc_co_u32_e32 v93, vcc, 0, v91, vcc
	v_add_co_u32_e32 v94, vcc, s24, v90
	s_min_i32 s27, s27, 0x55ff
	s_nop 0
	v_addc_co_u32_e32 v95, vcc, 0, v91, vcc
	global_load_dwordx4 v[90:93], v[92:93], off nt
	s_nop 0
	global_load_dwordx4 v[94:97], v[94:95], off nt
	s_ashr_i32 s29, s28, 31
	s_lshr_b32 s29, s29, 25
	v_add_u32_e32 v99, v117, v118
	s_add_i32 s29, s28, s29
	v_add_u32_e32 v106, 0x420, v99
	v_add_u32_e32 v107, 0x428, v99
	v_add_u32_e32 v108, 0x840, v99
	v_add_u32_e32 v109, 0x848, v99
	v_add_u32_e32 v110, 0xc60, v99
	v_add_u32_e32 v111, 0xc68, v99
	v_add_u32_e32 v112, 0x1080, v99
	v_add_u32_e32 v113, 0x1088, v99
	v_add_u32_e32 v114, 0x14a0, v99
	v_add_u32_e32 v115, 0x14a8, v99
	v_add_u32_e32 v123, 0x18c0, v99
	v_add_u32_e32 v124, 0x18c8, v99
	v_add_u32_e32 v125, 0x1ce0, v99
	v_add_u32_e32 v126, 0x1ce8, v99
	s_ashr_i32 s30, s29, 7
	s_and_b32 s29, s29, 0x7ffff80
	s_waitcnt vmcnt(17)
	ds_write2_b32 v99, v30, v31 offset1:1
	ds_write2_b32 v99, v32, v33 offset0:2 offset1:3
	ds_write2_b32 v106, v2, v3 offset1:1
	ds_write2_b32 v107, v4, v5 offset1:1
	ds_write2_b32 v108, v6, v7 offset1:1
	ds_write2_b32 v109, v8, v9 offset1:1
	ds_write2_b32 v110, v10, v11 offset1:1
	ds_write2_b32 v111, v12, v13 offset1:1
	ds_write2_b32 v112, v14, v15 offset1:1
	ds_write2_b32 v113, v16, v17 offset1:1
	ds_write2_b32 v114, v22, v23 offset1:1
	ds_write2_b32 v115, v24, v25 offset1:1
	ds_write2_b32 v123, v34, v35 offset1:1
	ds_write2_b32 v124, v36, v37 offset1:1
	s_waitcnt vmcnt(15)
	ds_write2_b32 v125, v42, v43 offset1:1
	ds_write2_b32 v126, v44, v45 offset1:1
	s_sub_i32 s28, s28, s29
	s_waitcnt lgkmcnt(0)
	s_lshl_b32 s31, s28, 5
	s_lshl_b32 s28, s30, 6
	v_or_b32_e32 v10, s31, v116
	ds_read2_b32 v[240:241], v122 offset1:33
	ds_read2_b32 v[242:243], v122 offset0:66 offset1:99
	ds_read2_b32 v[244:245], v122 offset0:132 offset1:165
	ds_read2_b32 v[246:247], v122 offset0:198 offset1:231
	ds_read2_b32 v[248:249], v122 offset0:8 offset1:41
	ds_read2_b32 v[250:251], v122 offset0:74 offset1:107
	ds_read2_b32 v[252:253], v122 offset0:140 offset1:173
	ds_read2_b32 v[254:255], v122 offset0:206 offset1:239
	s_ashr_i32 s29, s28, 31
	v_mul_lo_u32 v10, v10, s26
	s_waitcnt lgkmcnt(7)
	v_cvt_pk_bf16_f32 v2, v240, v241
	ds_read2_b32 v[240:241], v122 offset0:16 offset1:49
	v_lshl_add_u64 v[8:9], s[28:29], 1, v[104:105]
	v_ashrrev_i32_e32 v11, 31, v10
	s_waitcnt lgkmcnt(7)
	v_cvt_pk_bf16_f32 v3, v242, v243
	ds_read2_b32 v[242:243], v122 offset0:82 offset1:115
	v_lshl_add_u64 v[10:11], v[8:9], 0, v[10:11]
	s_waitcnt lgkmcnt(7)
	v_cvt_pk_bf16_f32 v4, v244, v245
	ds_read2_b32 v[244:245], v122 offset0:148 offset1:181
	s_waitcnt lgkmcnt(7)
	v_cvt_pk_bf16_f32 v5, v246, v247
	ds_read2_b32 v[246:247], v122 offset0:214 offset1:247
	global_store_dwordx4 v[10:11], v[2:5], off
	v_or_b32_e32 v10, s31, v119
	v_mul_lo_u32 v10, v10, s26
	s_waitcnt lgkmcnt(7)
	v_cvt_pk_bf16_f32 v2, v248, v249
	ds_read2_b32 v[248:249], v122 offset0:24 offset1:57
	v_ashrrev_i32_e32 v11, 31, v10
	s_waitcnt lgkmcnt(7)
	v_cvt_pk_bf16_f32 v3, v250, v251
	ds_read2_b32 v[250:251], v122 offset0:90 offset1:123
	v_lshl_add_u64 v[10:11], v[8:9], 0, v[10:11]
	s_waitcnt lgkmcnt(7)
	v_cvt_pk_bf16_f32 v4, v252, v253
	ds_read2_b32 v[252:253], v122 offset0:156 offset1:189
	s_waitcnt lgkmcnt(7)
	v_cvt_pk_bf16_f32 v5, v254, v255
	ds_read2_b32 v[254:255], v122 offset0:222 offset1:255
	global_store_dwordx4 v[10:11], v[2:5], off
	v_or_b32_e32 v10, s31, v120
	s_waitcnt lgkmcnt(7)
	v_cvt_pk_bf16_f32 v2, v240, v241
	v_mul_lo_u32 v10, v10, s26
	s_waitcnt lgkmcnt(6)
	v_cvt_pk_bf16_f32 v3, v242, v243
	v_ashrrev_i32_e32 v11, 31, v10
	s_waitcnt lgkmcnt(5)
	v_cvt_pk_bf16_f32 v4, v244, v245
	s_waitcnt lgkmcnt(4)
	v_cvt_pk_bf16_f32 v5, v246, v247
	v_lshl_add_u64 v[10:11], v[8:9], 0, v[10:11]
	global_store_dwordx4 v[10:11], v[2:5], off
	s_waitcnt lgkmcnt(3)
	s_nop 0
	v_cvt_pk_bf16_f32 v2, v248, v249
	s_waitcnt lgkmcnt(2)
	v_cvt_pk_bf16_f32 v3, v250, v251
	s_waitcnt lgkmcnt(1)
	v_cvt_pk_bf16_f32 v4, v252, v253
	s_waitcnt lgkmcnt(0)
	v_cvt_pk_bf16_f32 v5, v254, v255
	v_or_b32_e32 v6, s31, v121
	v_mul_lo_u32 v6, v6, s26
	v_ashrrev_i32_e32 v7, 31, v6
	v_lshl_add_u64 v[6:7], v[8:9], 0, v[6:7]
	global_store_dwordx4 v[6:7], v[2:5], off
	s_waitcnt lgkmcnt(0)
; #define LAS __attribute__((address_space(3)))
; __device__ __forceinline__ void p0_item_load(const float* __restrict__ W, int N, int nblk, int nb0, int item, int lane, f32x4 (&v)[8]) {
;     const int kb = item / nblk, nb = nb0 + item % nblk;
;     const float* src = W + (size_t)(64 * kb + (lane >> 3)) * N + 32 * nb + 4 * (lane & 7);
; #pragma unroll
;     for (int i = 0; i < 8; ++i) v[i] = __builtin_nontemporal_load((const f32x4*)(src + (size_t)(8 * i) * N));
; }
; __device__ __forceinline__ void p0_item_store(const f32x4 (&v)[8], int K, int nblk, int nb0, bf16* __restrict__ WT, int mode, LAS float* scr, int item, int lane) {
;     const int kb = item / nblk, nb = nb0 + item % nblk, k0 = 64 * kb, n0 = 32 * nb;
; #pragma unroll
;     for (int i = 0; i < 8; ++i) { LAS float* d = scr + (8 * i + (lane >> 3)) * 33 + 4 * (lane & 7); d[0] = v[i].x; d[1] = v[i].y; d[2] = v[i].z; d[3] = v[i].w; }
;     LDS_WAIT(); asm volatile("" ::: "memory");
;     const int c = lane & 7, r0 = map_row(n0, mode);
;     const float wsc = mode == 1 ? 1.44269504089f : (mode == 2 ? 0.69314718056f : 1.0f);
; #pragma unroll
;     for (int j = 0; j < 4; ++j) { const int n = (lane >> 3) + 8 * j; const LAS float* s = scr + (8 * c) * 33 + n;
;         v4u o; o.x = cvt_pk_bf16(s[0 * 33] * wsc, s[1 * 33] * wsc); o.y = cvt_pk_bf16(s[2 * 33] * wsc, s[3 * 33] * wsc); o.z = cvt_pk_bf16(s[4 * 33] * wsc, s[5 * 33] * wsc); o.w = cvt_pk_bf16(s[6 * 33] * wsc, s[7 * 33] * wsc);
;         *(v4u*)(WT + (size_t)(r0 + n) * K + k0 + 8 * c) = o; }
;     LDS_WAIT(); asm volatile("" ::: "memory");
; }
;     LAS float* scr = (LAS float*)(F.lds + RING_OFF + F.wave * 16384);
;     const int nblk = nbn ? nbn : N / 32, nall = (K / 64) * nblk, nitems = (int)((long)nall * f1 / 16);
;     int it = (int)((long)nall * f0 / 16) + w0; if (it >= nitems) return;
;     f32x4 va[8], vb[8], vc[8];
;     __builtin_amdgcn_s_waitcnt(0x0F70);
;     const int last = nitems - 1, ntri = ((nitems - it + nw - 1) / nw + 2) / 3;
;     int i1 = min(it + nw, last);
;     p0_item_load(W, N, nblk, nb0, it, F.lane, va);
;     p0_item_load(W, N, nblk, nb0, i1, F.lane, vb); __builtin_amdgcn_sched_barrier(0);
;     for (int p = 0; p < ntri; ++p) {
;         const int i2 = min(i1 + nw, last), i3 = min(i2 + nw, last), i4 = min(i3 + nw, last);
;         p0_item_load(W, N, nblk, nb0, i2, F.lane, vc); __builtin_amdgcn_sched_barrier(0);
	s_ashr_i32 s28, s3, 31
	s_lshr_b32 s28, s28, 25
	s_add_i32 s28, s3, s28
	s_ashr_i32 s29, s28, 7
	s_and_b32 s28, s28, 0x7ffff80
	v_lshl_or_b32 v2, s29, 6, v116
	s_sub_i32 s28, s3, s28
	v_ashrrev_i32_e32 v3, 31, v2
	v_lshlrev_b64 v[2:3], 14, v[2:3]
	s_lshl_b32 s28, s28, 5
	v_lshl_add_u64 v[2:3], s[86:87], 0, v[2:3]
	s_ashr_i32 s29, s28, 31
	v_lshl_add_u64 v[2:3], s[28:29], 2, v[2:3]
	v_lshl_add_u64 v[34:35], v[2:3], 0, v[100:101]
	v_add_co_u32_e32 v2, vcc, s10, v34
	s_nop 1
	v_addc_co_u32_e32 v3, vcc, 0, v35, vcc
	v_add_co_u32_e32 v6, vcc, s11, v34
	global_load_dwordx4 v[30:33], v[34:35], off nt
	s_nop 0
	global_load_dwordx4 v[2:5], v[2:3], off nt
	v_addc_co_u32_e32 v7, vcc, 0, v35, vcc
	v_add_co_u32_e32 v10, vcc, s12, v34
	s_nop 1
	v_addc_co_u32_e32 v11, vcc, 0, v35, vcc
	v_add_co_u32_e32 v14, vcc, s13, v34
	global_load_dwordx4 v[6:9], v[6:7], off nt
	s_nop 0
	global_load_dwordx4 v[10:13], v[10:11], off nt
	v_addc_co_u32_e32 v15, vcc, 0, v35, vcc
	v_add_co_u32_e32 v22, vcc, s14, v34
	s_nop 1
	v_addc_co_u32_e32 v23, vcc, 0, v35, vcc
	v_add_co_u32_e32 v36, vcc, s15, v34
	global_load_dwordx4 v[14:17], v[14:15], off nt
	s_nop 0
	global_load_dwordx4 v[22:25], v[22:23], off nt
	v_addc_co_u32_e32 v37, vcc, 0, v35, vcc
	v_add_co_u32_e32 v42, vcc, s24, v34
	s_nop 1
	v_addc_co_u32_e32 v43, vcc, 0, v35, vcc
	global_load_dwordx4 v[34:37], v[36:37], off nt
	s_nop 0
	global_load_dwordx4 v[42:45], v[42:43], off nt
	s_ashr_i32 s28, s5, 31
	s_lshr_b32 s28, s28, 25
	s_add_i32 s28, s5, s28
	s_ashr_i32 s29, s28, 7
	s_and_b32 s28, s28, 0x7ffff80
	ds_write2_b32 v99, v18, v19 offset1:1
	ds_write2_b32 v99, v20, v21 offset0:2 offset1:3
	s_waitcnt vmcnt(26)
	ds_write2_b32 v106, v26, v27 offset1:1
	ds_write2_b32 v107, v28, v29 offset1:1
	s_waitcnt vmcnt(25)
	ds_write2_b32 v108, v38, v39 offset1:1
	ds_write2_b32 v109, v40, v41 offset1:1
	s_waitcnt vmcnt(24)
	ds_write2_b32 v110, v46, v47 offset1:1
	ds_write2_b32 v111, v48, v49 offset1:1
	s_waitcnt vmcnt(23)
	ds_write2_b32 v112, v50, v51 offset1:1
	ds_write2_b32 v113, v52, v53 offset1:1
	s_waitcnt vmcnt(22)
	ds_write2_b32 v114, v54, v55 offset1:1
	ds_write2_b32 v115, v56, v57 offset1:1
	s_waitcnt vmcnt(21)
	ds_write2_b32 v123, v58, v59 offset1:1
	ds_write2_b32 v124, v60, v61 offset1:1
	s_waitcnt vmcnt(20)
	ds_write2_b32 v125, v62, v63 offset1:1
	ds_write2_b32 v126, v64, v65 offset1:1
	s_sub_i32 s5, s5, s28
	s_waitcnt lgkmcnt(0)
	s_lshl_b32 s5, s5, 5
	s_lshl_b32 s28, s29, 6
	v_or_b32_e32 v38, s5, v116
	ds_read2_b32 v[240:241], v122 offset1:33
	ds_read2_b32 v[242:243], v122 offset0:66 offset1:99
	ds_read2_b32 v[244:245], v122 offset0:132 offset1:165
	ds_read2_b32 v[246:247], v122 offset0:198 offset1:231
	ds_read2_b32 v[248:249], v122 offset0:8 offset1:41
	ds_read2_b32 v[250:251], v122 offset0:74 offset1:107
	ds_read2_b32 v[252:253], v122 offset0:140 offset1:173
	ds_read2_b32 v[254:255], v122 offset0:206 offset1:239
	s_ashr_i32 s29, s28, 31
	v_mul_lo_u32 v38, v38, s26
	s_waitcnt lgkmcnt(7)
	v_cvt_pk_bf16_f32 v18, v240, v241
	ds_read2_b32 v[240:241], v122 offset0:16 offset1:49
	v_lshl_add_u64 v[28:29], s[28:29], 1, v[104:105]
	v_ashrrev_i32_e32 v39, 31, v38
	s_waitcnt lgkmcnt(7)
	v_cvt_pk_bf16_f32 v19, v242, v243
	ds_read2_b32 v[242:243], v122 offset0:82 offset1:115
	v_lshl_add_u64 v[38:39], v[28:29], 0, v[38:39]
	s_waitcnt lgkmcnt(7)
	v_cvt_pk_bf16_f32 v20, v244, v245
	ds_read2_b32 v[244:245], v122 offset0:148 offset1:181
	s_waitcnt lgkmcnt(7)
	v_cvt_pk_bf16_f32 v21, v246, v247
	ds_read2_b32 v[246:247], v122 offset0:214 offset1:247
	global_store_dwordx4 v[38:39], v[18:21], off
	v_or_b32_e32 v38, s5, v119
	v_mul_lo_u32 v38, v38, s26
	s_waitcnt lgkmcnt(7)
	v_cvt_pk_bf16_f32 v18, v248, v249
	ds_read2_b32 v[248:249], v122 offset0:24 offset1:57
	v_ashrrev_i32_e32 v39, 31, v38
	s_waitcnt lgkmcnt(7)
	v_cvt_pk_bf16_f32 v19, v250, v251
	ds_read2_b32 v[250:251], v122 offset0:90 offset1:123
	v_lshl_add_u64 v[38:39], v[28:29], 0, v[38:39]
	s_waitcnt lgkmcnt(7)
	v_cvt_pk_bf16_f32 v20, v252, v253
	ds_read2_b32 v[252:253], v122 offset0:156 offset1:189
	s_waitcnt lgkmcnt(7)
	v_cvt_pk_bf16_f32 v21, v254, v255
	ds_read2_b32 v[254:255], v122 offset0:222 offset1:255
	global_store_dwordx4 v[38:39], v[18:21], off
	v_or_b32_e32 v38, s5, v120
	s_waitcnt lgkmcnt(7)
	v_cvt_pk_bf16_f32 v18, v240, v241
	v_mul_lo_u32 v38, v38, s26
	s_waitcnt lgkmcnt(6)
	v_cvt_pk_bf16_f32 v19, v242, v243
	v_ashrrev_i32_e32 v39, 31, v38
	s_waitcnt lgkmcnt(5)
	v_cvt_pk_bf16_f32 v20, v244, v245
	s_waitcnt lgkmcnt(4)
	v_cvt_pk_bf16_f32 v21, v246, v247
	v_lshl_add_u64 v[38:39], v[28:29], 0, v[38:39]
	global_store_dwordx4 v[38:39], v[18:21], off
	s_waitcnt lgkmcnt(3)
	s_nop 0
	v_cvt_pk_bf16_f32 v18, v248, v249
	s_waitcnt lgkmcnt(2)
	v_cvt_pk_bf16_f32 v19, v250, v251
	s_waitcnt lgkmcnt(1)
	v_cvt_pk_bf16_f32 v20, v252, v253
	v_or_b32_e32 v21, s5, v121
	v_mul_lo_u32 v38, v21, s26
	v_ashrrev_i32_e32 v39, 31, v38
	s_waitcnt lgkmcnt(0)
	v_cvt_pk_bf16_f32 v21, v254, v255
	v_lshl_add_u64 v[26:27], v[28:29], 0, v[38:39]
	global_store_dwordx4 v[26:27], v[18:21], off
	s_waitcnt lgkmcnt(0)
; #define LAS __attribute__((address_space(3)))
; __device__ __forceinline__ void p0_item_load(const float* __restrict__ W, int N, int nblk, int nb0, int item, int lane, f32x4 (&v)[8]) {
;     const int kb = item / nblk, nb = nb0 + item % nblk;
;     const float* src = W + (size_t)(64 * kb + (lane >> 3)) * N + 32 * nb + 4 * (lane & 7);
; #pragma unroll
;     for (int i = 0; i < 8; ++i) v[i] = __builtin_nontemporal_load((const f32x4*)(src + (size_t)(8 * i) * N));
; }
; __device__ __forceinline__ void p0_item_store(const f32x4 (&v)[8], int K, int nblk, int nb0, bf16* __restrict__ WT, int mode, LAS float* scr, int item, int lane) {
;     const int kb = item / nblk, nb = nb0 + item % nblk, k0 = 64 * kb, n0 = 32 * nb;
; #pragma unroll
;     for (int i = 0; i < 8; ++i) { LAS float* d = scr + (8 * i + (lane >> 3)) * 33 + 4 * (lane & 7); d[0] = v[i].x; d[1] = v[i].y; d[2] = v[i].z; d[3] = v[i].w; }
;     LDS_WAIT(); asm volatile("" ::: "memory");
;     const int c = lane & 7, r0 = map_row(n0, mode);
;     const float wsc = mode == 1 ? 1.44269504089f : (mode == 2 ? 0.69314718056f : 1.0f);
; #pragma unroll
;     for (int j = 0; j < 4; ++j) { const int n = (lane >> 3) + 8 * j; const LAS float* s = scr + (8 * c) * 33 + n;
;         v4u o; o.x = cvt_pk_bf16(s[0 * 33] * wsc, s[1 * 33] * wsc); o.y = cvt_pk_bf16(s[2 * 33] * wsc, s[3 * 33] * wsc); o.z = cvt_pk_bf16(s[4 * 33] * wsc, s[5 * 33] * wsc); o.w = cvt_pk_bf16(s[6 * 33] * wsc, s[7 * 33] * wsc);
;         *(v4u*)(WT + (size_t)(r0 + n) * K + k0 + 8 * c) = o; }
;     LDS_WAIT(); asm volatile("" ::: "memory");
; }
;     LAS float* scr = (LAS float*)(F.lds + RING_OFF + F.wave * 16384);
;     const int nblk = nbn ? nbn : N / 32, nall = (K / 64) * nblk, nitems = (int)((long)nall * f1 / 16);
;     int it = (int)((long)nall * f0 / 16) + w0; if (it >= nitems) return;
;     f32x4 va[8], vb[8], vc[8];
;     __builtin_amdgcn_s_waitcnt(0x0F70);
;     const int last = nitems - 1, ntri = ((nitems - it + nw - 1) / nw + 2) / 3;
;     int i1 = min(it + nw, last);
;     p0_item_load(W, N, nblk, nb0, it, F.lane, va);
;     p0_item_load(W, N, nblk, nb0, i1, F.lane, vb); __builtin_amdgcn_sched_barrier(0);
;     for (int p = 0; p < ntri; ++p) {
;         const int i2 = min(i1 + nw, last), i3 = min(i2 + nw, last), i4 = min(i3 + nw, last);
;         p0_item_load(W, N, nblk, nb0, i2, F.lane, vc); __builtin_amdgcn_sched_barrier(0);
	s_ashr_i32 s5, s27, 31
	s_lshr_b32 s5, s5, 25
	s_add_i32 s5, s27, s5
	s_ashr_i32 s28, s5, 7
	s_and_b32 s5, s5, 0x7ffff80
	v_lshl_or_b32 v18, s28, 6, v116
	s_sub_i32 s5, s27, s5
	v_ashrrev_i32_e32 v19, 31, v18
	v_lshlrev_b64 v[18:19], 14, v[18:19]
	s_lshl_b32 s28, s5, 5
	v_lshl_add_u64 v[18:19], s[86:87], 0, v[18:19]
	s_ashr_i32 s29, s28, 31
	v_lshl_add_u64 v[18:19], s[28:29], 2, v[18:19]
	v_lshl_add_u64 v[58:59], v[18:19], 0, v[100:101]
	v_add_co_u32_e32 v26, vcc, s10, v58
	s_nop 1
	v_addc_co_u32_e32 v27, vcc, 0, v59, vcc
	v_add_co_u32_e32 v38, vcc, s11, v58
	global_load_dwordx4 v[18:21], v[58:59], off nt
	s_nop 0
	global_load_dwordx4 v[26:29], v[26:27], off nt
	v_addc_co_u32_e32 v39, vcc, 0, v59, vcc
	v_add_co_u32_e32 v46, vcc, s12, v58
	s_nop 1
	v_addc_co_u32_e32 v47, vcc, 0, v59, vcc
	v_add_co_u32_e32 v50, vcc, s13, v58
	global_load_dwordx4 v[38:41], v[38:39], off nt
	s_nop 0
	global_load_dwordx4 v[46:49], v[46:47], off nt
	v_addc_co_u32_e32 v51, vcc, 0, v59, vcc
	v_add_co_u32_e32 v54, vcc, s14, v58
	s_nop 1
	v_addc_co_u32_e32 v55, vcc, 0, v59, vcc
	v_add_co_u32_e32 v60, vcc, s15, v58
	global_load_dwordx4 v[50:53], v[50:51], off nt
	s_nop 0
	global_load_dwordx4 v[54:57], v[54:55], off nt
	v_addc_co_u32_e32 v61, vcc, 0, v59, vcc
	v_add_co_u32_e32 v62, vcc, s24, v58
	s_nop 1
	v_addc_co_u32_e32 v63, vcc, 0, v59, vcc
	global_load_dwordx4 v[58:61], v[60:61], off nt
	s_nop 0
	global_load_dwordx4 v[62:65], v[62:63], off nt
	s_waitcnt vmcnt(31)
	ds_write2_b32 v99, v66, v67 offset1:1
	ds_write2_b32 v99, v68, v69 offset0:2 offset1:3
	s_waitcnt vmcnt(30)
	ds_write2_b32 v106, v70, v71 offset1:1
	ds_write2_b32 v107, v72, v73 offset1:1
	s_waitcnt vmcnt(29)
	ds_write2_b32 v108, v74, v75 offset1:1
	ds_write2_b32 v109, v76, v77 offset1:1
	s_waitcnt vmcnt(28)
	ds_write2_b32 v110, v78, v79 offset1:1
	ds_write2_b32 v111, v80, v81 offset1:1
	s_waitcnt vmcnt(27)
	ds_write2_b32 v112, v82, v83 offset1:1
	ds_write2_b32 v113, v84, v85 offset1:1
	s_waitcnt vmcnt(26)
	ds_write2_b32 v114, v86, v87 offset1:1
	ds_write2_b32 v115, v88, v89 offset1:1
	s_waitcnt vmcnt(25)
	ds_write2_b32 v123, v90, v91 offset1:1
	ds_write2_b32 v124, v92, v93 offset1:1
	s_waitcnt vmcnt(24)
	ds_write2_b32 v125, v94, v95 offset1:1
	ds_write2_b32 v126, v96, v97 offset1:1
	s_waitcnt lgkmcnt(0)
	v_or_b32_e32 v74, s2, v116
	ds_read2_b32 v[240:241], v122 offset1:33
	ds_read2_b32 v[242:243], v122 offset0:66 offset1:99
	ds_read2_b32 v[244:245], v122 offset0:132 offset1:165
	ds_read2_b32 v[246:247], v122 offset0:198 offset1:231
	ds_read2_b32 v[248:249], v122 offset0:8 offset1:41
	ds_read2_b32 v[250:251], v122 offset0:74 offset1:107
	ds_read2_b32 v[252:253], v122 offset0:140 offset1:173
	ds_read2_b32 v[254:255], v122 offset0:206 offset1:239
	s_ashr_i32 s5, s4, 31
	v_mul_lo_u32 v74, v74, s26
	s_waitcnt lgkmcnt(7)
	v_cvt_pk_bf16_f32 v66, v240, v241
	ds_read2_b32 v[240:241], v122 offset0:16 offset1:49
	v_lshl_add_u64 v[72:73], s[4:5], 1, v[104:105]
	v_ashrrev_i32_e32 v75, 31, v74
	s_waitcnt lgkmcnt(7)
	v_cvt_pk_bf16_f32 v67, v242, v243
	ds_read2_b32 v[242:243], v122 offset0:82 offset1:115
	v_lshl_add_u64 v[74:75], v[72:73], 0, v[74:75]
	s_waitcnt lgkmcnt(7)
	v_cvt_pk_bf16_f32 v68, v244, v245
	ds_read2_b32 v[244:245], v122 offset0:148 offset1:181
	s_waitcnt lgkmcnt(7)
	v_cvt_pk_bf16_f32 v69, v246, v247
	ds_read2_b32 v[246:247], v122 offset0:214 offset1:247
	global_store_dwordx4 v[74:75], v[66:69], off
	v_or_b32_e32 v74, s2, v119
	v_mul_lo_u32 v74, v74, s26
	s_waitcnt lgkmcnt(7)
	v_cvt_pk_bf16_f32 v66, v248, v249
	ds_read2_b32 v[248:249], v122 offset0:24 offset1:57
	v_ashrrev_i32_e32 v75, 31, v74
	s_waitcnt lgkmcnt(7)
	v_cvt_pk_bf16_f32 v67, v250, v251
	ds_read2_b32 v[250:251], v122 offset0:90 offset1:123
	v_lshl_add_u64 v[74:75], v[72:73], 0, v[74:75]
	s_waitcnt lgkmcnt(7)
	v_cvt_pk_bf16_f32 v68, v252, v253
	ds_read2_b32 v[252:253], v122 offset0:156 offset1:189
	s_waitcnt lgkmcnt(7)
	v_cvt_pk_bf16_f32 v69, v254, v255
	ds_read2_b32 v[254:255], v122 offset0:222 offset1:255
	global_store_dwordx4 v[74:75], v[66:69], off
	v_or_b32_e32 v74, s2, v120
	s_waitcnt lgkmcnt(7)
	v_cvt_pk_bf16_f32 v66, v240, v241
	v_mul_lo_u32 v74, v74, s26
	s_waitcnt lgkmcnt(6)
	v_cvt_pk_bf16_f32 v67, v242, v243
	v_ashrrev_i32_e32 v75, 31, v74
	s_waitcnt lgkmcnt(5)
	v_cvt_pk_bf16_f32 v68, v244, v245
	s_waitcnt lgkmcnt(4)
	v_cvt_pk_bf16_f32 v69, v246, v247
	v_lshl_add_u64 v[74:75], v[72:73], 0, v[74:75]
	global_store_dwordx4 v[74:75], v[66:69], off
	s_waitcnt lgkmcnt(3)
	s_nop 0
	v_cvt_pk_bf16_f32 v66, v248, v249
	s_waitcnt lgkmcnt(2)
	v_cvt_pk_bf16_f32 v67, v250, v251
	s_waitcnt lgkmcnt(1)
	v_cvt_pk_bf16_f32 v68, v252, v253
	v_or_b32_e32 v69, s2, v121
	v_mul_lo_u32 v74, v69, s26
	v_ashrrev_i32_e32 v75, 31, v74
	s_waitcnt lgkmcnt(0)
	v_cvt_pk_bf16_f32 v69, v254, v255
	v_lshl_add_u64 v[70:71], v[72:73], 0, v[74:75]
	global_store_dwordx4 v[70:71], v[66:69], off
	s_waitcnt lgkmcnt(0)
	s_add_i32 s25, s25, -1
	s_cmp_lg_u32 s25, 0
	s_mov_b32 s28, s3
	s_mov_b32 s5, s27
	s_cbranch_scc1 .LBB0_101
; #define LAS __attribute__((address_space(3)))
;     LAS float* scr = (LAS float*)(F.lds + RING_OFF + F.wave * 16384);
;     const int nblk = nbn ? nbn : N / 32, nall = (K / 64) * nblk, nitems = (int)((long)nall * f1 / 16);
;     int it = (int)((long)nall * f0 / 16) + w0; if (it >= nitems) return;
;     f32x4 va[8], vb[8], vc[8];
;     __builtin_amdgcn_s_waitcnt(0x0F70);
;     const int last = nitems - 1, ntri = ((nitems - it + nw - 1) / nw + 2) / 3;
;     int i1 = min(it + nw, last);
;     p0_item_load(W, N, nblk, nb0, it, F.lane, va);
;     p0_item_load(W, N, nblk, nb0, i1, F.lane, vb); __builtin_amdgcn_sched_barrier(0);
; __device__ __forceinline__ void convert_beside_ffn1(Frame& F, const Args& A, int w0, int nw) {
;     ...
;     p0_transpose(F, A.in[7], DFF, D, (bf16*)(F.ws + WS_WD1), 0, w0, nw);
;     p0_transpose(F, A.in[9], D, INW, (bf16*)(F.ws + WS_WIN), 0, w0, nw);
.LBB0_102:
	s_cmpk_gt_i32 s18, 0x6fff
	s_cbranch_scc1 .LBB0_106
	s_mul_hi_i32 s2, s18, 0x92492493
	s_add_i32 s2, s2, s18
	s_lshr_b32 s3, s2, 31
	s_ashr_i32 s2, s2, 8
	v_readlane_b32 s36, v236, 20
	s_add_i32 s2, s2, s3
	v_readlane_b32 s38, v236, 22
	v_readlane_b32 s39, v236, 23
	s_mul_i32 s3, s2, 0x1c0
	s_waitcnt vmcnt(15)
	v_lshl_or_b32 v4, s2, 6, v116
	s_mov_b32 s10, 0xe000
	v_mov_b64_e32 v[2:3], s[38:39]
	s_sub_i32 s4, s18, s3
	v_mad_i64_i32 v[4:5], s[2:3], v4, s10, v[2:3]
	s_lshl_b32 s2, s4, 5
	s_min_i32 s5, s23, 0x6fff
	s_ashr_i32 s3, s2, 31
	v_lshl_add_u64 v[4:5], s[2:3], 2, v[4:5]
	s_mul_hi_i32 s2, s5, 0x92492493
	s_add_i32 s2, s2, s5
	s_lshr_b32 s3, s2, 31
	s_ashr_i32 s2, s2, 8
	v_mov_b32_e32 v101, 0
	s_add_i32 s2, s2, s3
	s_waitcnt vmcnt(8)
	v_lshl_add_u64 v[18:19], v[4:5], 0, v[100:101]
	s_mul_i32 s3, s2, 0x1c0
	v_lshl_or_b32 v4, s2, 6, v116
	s_sub_i32 s4, s5, s3
	v_mad_i64_i32 v[2:3], s[2:3], v4, s10, v[2:3]
	s_lshl_b32 s2, s4, 5
	s_ashr_i32 s3, s2, 31
	v_lshl_add_u64 v[2:3], s[2:3], 2, v[2:3]
	s_mov_b32 s11, 0x70000
	s_waitcnt vmcnt(1)
	v_lshl_add_u64 v[58:59], v[2:3], 0, v[100:101]
	v_add_co_u32_e32 v2, vcc, s11, v18
	s_mov_b32 s12, 0xe0000
	s_nop 0
	v_addc_co_u32_e32 v3, vcc, 0, v19, vcc
	v_add_co_u32_e32 v6, vcc, s12, v18
	s_mov_b32 s13, 0x150000
	s_nop 0
	v_addc_co_u32_e32 v7, vcc, 0, v19, vcc
	v_add_co_u32_e32 v10, vcc, s13, v18
	s_mov_b32 s14, 0x1c0000
	s_nop 0
	v_addc_co_u32_e32 v11, vcc, 0, v19, vcc
	v_add_co_u32_e32 v14, vcc, s14, v18
	s_mov_b32 s15, 0x230000
	s_nop 0
	v_addc_co_u32_e32 v15, vcc, 0, v19, vcc
	v_add_co_u32_e32 v20, vcc, s15, v18
	s_mov_b32 s24, 0x2a0000
	s_nop 0
	v_addc_co_u32_e32 v21, vcc, 0, v19, vcc
	v_add_co_u32_e32 v26, vcc, s24, v18
	s_mov_b32 s25, 0x310000
	s_nop 0
	v_addc_co_u32_e32 v27, vcc, 0, v19, vcc
	s_waitcnt vmcnt(0)
	global_load_dwordx4 v[2:5], v[2:3], off nt
	s_nop 0
	global_load_dwordx4 v[6:9], v[6:7], off nt
	s_nop 0
	global_load_dwordx4 v[10:13], v[10:11], off nt
	s_nop 0
	global_load_dwordx4 v[14:17], v[14:15], off nt
	s_nop 0
	global_load_dwordx4 v[22:25], v[20:21], off nt
	global_load_dwordx4 v[34:37], v[26:27], off nt
	v_add_co_u32_e32 v26, vcc, s25, v18
	s_add_i32 s2, s19, 0x68ff
	s_nop 0
	v_addc_co_u32_e32 v27, vcc, 0, v19, vcc
	v_add_co_u32_e32 v28, vcc, s11, v58
	global_load_dwordx4 v[30:33], v[18:19], off nt
	s_nop 0
	global_load_dwordx4 v[18:21], v[58:59], off nt
	v_addc_co_u32_e32 v29, vcc, 0, v59, vcc
	v_add_co_u32_e32 v38, vcc, s12, v58
	global_load_dwordx4 v[42:45], v[26:27], off nt
	s_nop 0
	global_load_dwordx4 v[26:29], v[28:29], off nt
	v_addc_co_u32_e32 v39, vcc, 0, v59, vcc
	v_add_co_u32_e32 v46, vcc, s13, v58
	s_sub_i32 s4, 0xffff9701, s19
	s_nop 0
	v_addc_co_u32_e32 v47, vcc, 0, v59, vcc
	v_add_co_u32_e32 v50, vcc, s14, v58
	global_load_dwordx4 v[38:41], v[38:39], off nt
	s_nop 0
	global_load_dwordx4 v[46:49], v[46:47], off nt
	v_addc_co_u32_e32 v51, vcc, 0, v59, vcc
	v_add_co_u32_e32 v54, vcc, s15, v58
	s_ashr_i32 s3, s2, 31
	s_nop 0
	v_addc_co_u32_e32 v55, vcc, 0, v59, vcc
	v_add_co_u32_e32 v60, vcc, 0x2a0000, v58
	global_load_dwordx4 v[50:53], v[50:51], off nt
	s_nop 0
	global_load_dwordx4 v[54:57], v[54:55], off nt
	v_addc_co_u32_e32 v61, vcc, 0, v59, vcc
	v_add_co_u32_e32 v62, vcc, 0x310000, v58
	s_max_i32 s2, s2, s4
	s_nop 0
	v_addc_co_u32_e32 v63, vcc, 0, v59, vcc
	global_load_dwordx4 v[58:61], v[60:61], off nt
	s_nop 0
	global_load_dwordx4 v[62:65], v[62:63], off nt
	s_mul_hi_u32 s4, s2, s22
	s_mul_i32 s26, s4, s20
	s_sub_i32 s2, s2, s26
	s_xor_b32 s3, s3, s21
	s_add_i32 s26, s4, 1
	s_sub_i32 s27, s2, s20
	s_cmp_ge_u32 s2, s20
	s_cselect_b32 s4, s26, s4
	s_cselect_b32 s2, s27, s2
	s_add_i32 s26, s4, 1
	s_cmp_ge_u32 s2, s20
	s_cselect_b32 s2, s26, s4
	s_xor_b32 s2, s2, s3
	s_sub_i32 s2, s2, s3
	v_readlane_b32 s37, v236, 21
	v_readlane_b32 s40, v236, 24
	v_readlane_b32 s41, v236, 25
	v_readlane_b32 s42, v236, 26
	v_readlane_b32 s43, v236, 27
	v_readlane_b32 s44, v236, 28
	v_readlane_b32 s45, v236, 29
	v_readlane_b32 s46, v236, 30
	v_readlane_b32 s47, v236, 31
	v_readlane_b32 s48, v236, 32
	v_readlane_b32 s49, v236, 33
	v_readlane_b32 s50, v236, 34
	v_readlane_b32 s51, v236, 35
	s_cmp_lt_i32 s2, 1
	s_cbranch_scc1 .LBB0_106
	v_lshlrev_b32_e32 v66, 1, v98
	v_mov_b32_e32 v67, v101
	s_add_i32 s2, s2, 2
	v_lshl_add_u64 v[66:67], s[96:97], 0, v[66:67]
	s_mov_b64 s[26:27], 0x10e00000
	s_mul_hi_u32 s2, s2, 0xaaaaaaab
	v_readlane_b32 s36, v236, 20
	v_lshl_add_u64 v[104:105], v[66:67], 0, s[26:27]
	s_lshr_b32 s26, s2, 1
	s_mov_b32 s28, s18
	v_readlane_b32 s38, v236, 22
	v_readlane_b32 s39, v236, 23
	v_readlane_b32 s37, v236, 21
	v_readlane_b32 s40, v236, 24
	v_readlane_b32 s41, v236, 25
	v_readlane_b32 s42, v236, 26
	v_readlane_b32 s43, v236, 27
	v_readlane_b32 s44, v236, 28
	v_readlane_b32 s45, v236, 29
	v_readlane_b32 s46, v236, 30
	v_readlane_b32 s47, v236, 31
	v_readlane_b32 s48, v236, 32
	v_readlane_b32 s49, v236, 33
	v_readlane_b32 s50, v236, 34
	v_readlane_b32 s51, v236, 35

; __global__ void __launch_bounds__(NWAVES * 64, 2) mk_fwd(Args args) {
amdhsa.kernels:
  - .agpr_count:     0
    .args:
      - .offset:         0
        .size:           256
        .value_kind:     by_value
      - .offset:         256
        .size:           4
        .value_kind:     hidden_block_count_x
      - .offset:         260
        .size:           4
        .value_kind:     hidden_block_count_y
      - .offset:         264
        .size:           4
        .value_kind:     hidden_block_count_z
      - .offset:         268
        .size:           2
        .value_kind:     hidden_group_size_x
      - .offset:         270
        .size:           2
        .value_kind:     hidden_group_size_y
      - .offset:         272
        .size:           2
        .value_kind:     hidden_group_size_z
      - .offset:         274
        .size:           2
        .value_kind:     hidden_remainder_x
      - .offset:         276
        .size:           2
        .value_kind:     hidden_remainder_y
      - .offset:         278
        .size:           2
        .value_kind:     hidden_remainder_z
      - .offset:         296
        .size:           8
        .value_kind:     hidden_global_offset_x
      - .offset:         304
        .size:           8
        .value_kind:     hidden_global_offset_y
      - .offset:         312
        .size:           8
        .value_kind:     hidden_global_offset_z
      - .offset:         320
        .size:           2
        .value_kind:     hidden_grid_dims
      - .offset:         376
        .size:           4
        .value_kind:     hidden_dynamic_lds_size
    .group_segment_fixed_size: 0
    .kernarg_segment_align: 8
    .kernarg_segment_size: 512
    .language:       OpenCL C
    .language_version:
      - 2
      - 0
    .max_flat_workgroup_size: 512
    .name:           _Z6mk_fwd4Args
    .private_segment_fixed_size: 0
    .sgpr_count:     108
    .sgpr_spill_count: 86
    .symbol:         _Z6mk_fwd4Args.kd
    .uniform_work_group_size: 1
    .uses_dynamic_stack: false
    .vgpr_count:     256
    .vgpr_spill_count: 0
    .wavefront_size: 64
